# early buffer_wbl2 by mid arrivers (remaining==16 or 4) in XCD barrier
# baseline (speedup 1.0000x reference)
; __device__ __forceinline__ unsigned xb_ld(unsigned* p)              { return __hip_atomic_load(p, __ATOMIC_RELAXED, __HIP_MEMORY_SCOPE_AGENT); }
; __device__ __forceinline__ unsigned xb_add(unsigned* p, unsigned v) { return __hip_atomic_fetch_add(p, v, __ATOMIC_RELAXED, __HIP_MEMORY_SCOPE_AGENT); }
; #define XB_SPIN(cond, bar) do { unsigned _sp = 0; while (cond) { __builtin_amdgcn_s_sleep(1); \
;     if ((++_sp & 255u) == 0u) { if (xb_ld(&(bar)[XB_TMO])) break; if (_sp > XB_SPIN_CAP) { atomicAdd(&(bar)[XB_TMO], 1u); break; } } } } while (0)
; __device__ __forceinline__ void xcd_barrier(const XcdBarrier& b) {
;     ...
;         const unsigned old = xb_add(&bar[XB_XSUB(b.x)], 1u);
;         const unsigned gen = old / nloc;
;         if (old + 1u == (gen + 1u) * nloc) {
;             __builtin_amdgcn_fence(__ATOMIC_RELEASE, "agent");
;             asm volatile("s_waitcnt vmcnt(0)" ::: "memory");
;             const unsigned og = xb_add(&bar[XB_TOP], 1u);
;             const unsigned tg = og / nx;
;             if (og + 1u == (tg + 1u) * nx) xb_add(&bar[XB_TOPGEN], 1u);
;             else XB_SPIN(xb_ld(&bar[XB_TOPGEN]) == tg, bar);
;             __builtin_amdgcn_fence(__ATOMIC_ACQUIRE, "agent");
;             xb_add(&bar[XB_XGEN(b.x)], 1u);
;             asm volatile("s_waitcnt vmcnt(0)" ::: "memory");
;         } else {
;             XB_SPIN(xb_ld(&bar[XB_XGEN(b.x)]) == gen, bar);
.LBB0_1974:
	s_lshl_b32 s24, s33, 6
	s_add_i32 s56, s24, 0x500
	s_lshl_b64 s[4:5], s[56:57], 2
	s_add_u32 s4, s2, s4
	s_addc_u32 s5, s3, s5
	v_mov_b64_e32 v[4:5], s[4:5]
	v_mov_b32_e32 v1, 1
	flat_atomic_add v3, v[4:5], v1 sc0
	v_cvt_f32_u32_e32 v1, v2
	v_sub_u32_e32 v4, 0, v2
	v_rcp_iflag_f32_e32 v1, v1
	s_nop 0
	v_mul_f32_e32 v1, 0x4f7ffffe, v1
	v_cvt_u32_f32_e32 v1, v1
	v_mul_lo_u32 v4, v4, v1
	v_mul_hi_u32 v4, v1, v4
	v_add_u32_e32 v1, v1, v4
	s_waitcnt vmcnt(0) lgkmcnt(0)
	v_mul_hi_u32 v1, v3, v1
	v_mul_lo_u32 v4, v1, v2
	v_sub_u32_e32 v4, v3, v4
	v_cmp_ge_u32_e32 vcc, v4, v2
	v_add_u32_e32 v5, 1, v1
	s_nop 0
	v_cndmask_b32_e32 v1, v1, v5, vcc
	v_sub_u32_e32 v5, v4, v2
	v_cndmask_b32_e32 v4, v4, v5, vcc
	v_cmp_ge_u32_e32 vcc, v4, v2
	v_add_u32_e32 v4, 1, v1
	s_nop 0
	v_cndmask_b32_e32 v1, v1, v4, vcc
	v_add_u32_e32 v4, 1, v3
	v_mad_u64_u32 v[2:3], s[4:5], v2, v1, v[2:3]
	v_cmp_ne_u32_e32 vcc, v4, v2
	s_and_saveexec_b64 s[4:5], vcc
	s_xor_b64 s[4:5], exec, s[4:5]
	s_cbranch_execz .LBB0_1987
	v_sub_u32_e32 v0, v2, v4
	v_cmp_eq_u32_e32 vcc, 16, v0
	v_cmp_eq_u32_e64 s[6:7], 4, v0
	s_or_b64 vcc, vcc, s[6:7]
	s_cbranch_vccz .Lew_skip
	buffer_wbl2 sc1
.Lew_skip:
	s_add_i32 s56, s24, 0x900
	s_lshl_b64 s[6:7], s[56:57], 2
	s_add_u32 s8, s2, s6
	s_addc_u32 s9, s3, s7
	v_mov_b64_e32 v[2:3], s[8:9]
	flat_load_dword v0, v[2:3] sc1
	s_waitcnt vmcnt(0) lgkmcnt(0)
	v_cmp_eq_u32_e32 vcc, v0, v1
	s_and_saveexec_b64 s[6:7], vcc
	s_cbranch_execz .LBB0_1986
	s_mov_b32 s25, 1
	s_mov_b64 s[10:11], 0
	s_branch .LBB0_1978
